# flash C loop: two key halves interleaved with all K / V^T fragments prefetched (as D loop); replaces the C negm-copy edit
# speedup vs baseline: 1.0553x; 1.0031x over previous
; template <int DQK, int NSUB, int MODE>
; __device__ __forceinline__ void flash_unit(LAS char* L, const bf16_t* Qp, int qpitch, const bf16_t* Kp, int kpitch, const bf16_t* Vp, int vpitch,
;                                            bf16_t* Op, int opitch, float lam, float oscale, const float* subln) {
;     ...
;     for (int t = 0; t < SEQ / 64; ++t) {
;         const int buf = t & 1;
;         if (t + 1 < SEQ / 64) { const size_t ko = (size_t)(t + 1) * 64 * kpitch, vo = (size_t)(t + 1) * 64 * vpitch;
;             rk1 = *(const u32x4*)(kg1 + ko); if (has2) rk2 = *(const u32x4*)(kg2 + ko); rv1 = *(const u32x4*)(vg1 + vo); }
.LBB0_608:
	s_cmp_lg_u32 s12, 0x168000
	s_cselect_b64 s[14:15], -1, 0
	s_cmp_eq_u32 s12, 0x168000
	s_cbranch_scc1 .Lfc_612
	v_lshl_add_u64 v[220:221], v[124:125], 0, s[12:13]
	global_load_dwordx4 v[108:111], v[220:221], off
	s_and_saveexec_b64 s[8:9], s[36:37]
	s_cbranch_execz .Lfc_611
	v_lshl_add_u64 v[220:221], v[122:123], 0, s[12:13]
	global_load_dwordx4 v[104:107], v[220:221], off

; #define MFMA32(a, b, c) __builtin_amdgcn_mfma_f32_32x32x16_bf16((a), (b), (c), 0, 0, 0)
; template <int DQK, int NSUB, int MODE>
; __device__ __forceinline__ void flash_unit(LAS char* L, const bf16_t* Qp, int qpitch, const bf16_t* Kp, int kpitch, const bf16_t* Vp, int vpitch,
;                                            bf16_t* Op, int opitch, float lam, float oscale, const float* subln) {
;     ...
;         for (int s = 0; s < NSUB; ++s) {
;             f32x16 p0, p1;
; #pragma unroll
;             for (int d0 = 0; d0 < ND0; ++d0) { const bf16x8 k0 = *(const bf16x8*)(Kb + r32 * KPB + (s * DQK + 16 * d0 + 8 * hi) * 2); const bf16x8 k1 = *(const bf16x8*)(Kb + (32 + r32) * KPB + (s * DQK + 16 * d0 + 8 * hi) * 2);
;                 if (d0 == 0) { p0 = MFMA32(k0, qf[s][d0], negm[s]); p1 = MFMA32(k1, qf[s][d0], negm[s]); }
;                 else { p0 = MFMA32(k0, qf[s][d0], p0); p1 = MFMA32(k1, qf[s][d0], p1); } }
; #pragma unroll
;             for (int hf = 0; hf < 2; ++hf) {
;                 f32x16& ph = hf ? p1 : p0;
;                 float mx = fmaxf(ph[0], ph[1]);
; #pragma unroll
;                 for (int r = 2; r < 16; ++r) mx = fmaxf(mx, ph[r]);
;                 mx = fmaxf(mx, __shfl_xor(mx, 32));
;                 const bool first = (t == 0) && (hf == 0);
;                 if (first || __any(mx > 8.0f)) {
;                     const float dl = first ? mx : fmaxf(mx, 0.f); mref[s] += dl;
; #pragma unroll
;                     for (int r = 0; r < 16; ++r) { ph[r] -= dl; negm[s][r] = -mref[s]; }
;                     if (hf == 0) {
; #pragma unroll
;                         for (int r = 0; r < 16; ++r) p1[r] -= dl;
;                     }
;                     if (!first) { const float alpha = __builtin_amdgcn_exp2f(-dl); lrow[s] *= alpha;
; #pragma unroll
;                         for (int r = 0; r < 16; ++r) { o[s][0][r] *= alpha; o[s][1][r] *= alpha; } }
;                 }
.Lfc_612:
	s_and_b32 s8, s21, 1
	s_mul_i32 s9, s8, 0x3400
	v_add_u32_e32 v228, s9, v131
	s_mul_i32 s9, s8, 0x2400
	v_add_u32_e32 v229, s9, v130
	ds_read_b128 v[132:135], v228
	ds_read_b128 v[136:139], v228 offset:32
	ds_read_b128 v[144:147], v228 offset:64
	ds_read_b128 v[148:151], v228 offset:96
	ds_read_b128 v[152:155], v228 offset:128
	ds_read_b128 v[164:167], v228 offset:160
	ds_read_b128 v[168:171], v228 offset:6656
	ds_read_b128 v[172:175], v228 offset:6688
	ds_read_b128 v[176:179], v228 offset:6720
	ds_read_b128 v[180:183], v228 offset:6752
	ds_read_b128 v[196:199], v228 offset:6784
	ds_read_b128 v[200:203], v228 offset:6816
	s_waitcnt lgkmcnt(6)
	v_mfma_f32_32x32x16_bf16 v[64:79], v[132:135], v[100:103], v[32:47]
	v_mfma_f32_32x32x16_bf16 v[64:79], v[136:139], v[80:83], v[64:79]
	v_mfma_f32_32x32x16_bf16 v[64:79], v[144:147], v[84:87], v[64:79]
	v_mfma_f32_32x32x16_bf16 v[64:79], v[148:151], v[88:91], v[64:79]
	v_mfma_f32_32x32x16_bf16 v[64:79], v[152:155], v[92:95], v[64:79]
	v_mfma_f32_32x32x16_bf16 v[64:79], v[164:167], v[96:99], v[64:79]
	s_waitcnt lgkmcnt(0)
	v_mfma_f32_32x32x16_bf16 v[48:63], v[168:171], v[100:103], v[32:47]
	v_mfma_f32_32x32x16_bf16 v[48:63], v[172:175], v[80:83], v[48:63]
	ds_read_b64_tr_b16 v[204:205], v229 offset:26624
	ds_read_b64_tr_b16 v[206:207], v229 offset:27776
	ds_read_b64_tr_b16 v[208:209], v229 offset:28928
	ds_read_b64_tr_b16 v[210:211], v229 offset:30080
	ds_read_b64_tr_b16 v[212:213], v229 offset:26688
	ds_read_b64_tr_b16 v[214:215], v229 offset:27840
	ds_read_b64_tr_b16 v[216:217], v229 offset:28992
	ds_read_b64_tr_b16 v[218:219], v229 offset:30144
	ds_read_b64_tr_b16 v[132:133], v229 offset:31232
	ds_read_b64_tr_b16 v[134:135], v229 offset:32384
	ds_read_b64_tr_b16 v[136:137], v229 offset:33536
	ds_read_b64_tr_b16 v[138:139], v229 offset:34688
	ds_read_b64_tr_b16 v[144:145], v229 offset:31296
	ds_read_b64_tr_b16 v[146:147], v229 offset:32448
	ds_read_b64_tr_b16 v[148:149], v229 offset:33600
	ds_read_b64_tr_b16 v[150:151], v229 offset:34752
	v_max_f32_e32 v222, v65, v65
	v_max_f32_e32 v223, v64, v64
	v_max_f32_e32 v222, v223, v222
	v_mfma_f32_32x32x16_bf16 v[48:63], v[176:179], v[84:87], v[48:63]
	v_max3_f32 v222, v222, v66, v67
	v_max3_f32 v222, v222, v68, v69
	v_mfma_f32_32x32x16_bf16 v[48:63], v[180:183], v[88:91], v[48:63]
	v_max3_f32 v222, v222, v70, v71
	v_max3_f32 v222, v222, v72, v73
	v_mfma_f32_32x32x16_bf16 v[48:63], v[196:199], v[92:95], v[48:63]
	v_max3_f32 v222, v222, v74, v75
	v_max3_f32 v222, v222, v76, v77
	v_max3_f32 v222, v222, v78, v79
	v_mfma_f32_32x32x16_bf16 v[48:63], v[200:203], v[96:99], v[48:63]
	v_cmp_lt_f32_e32 vcc, s61, v222
	s_cbranch_vccz .Lfc_614
	ds_bpermute_b32 v223, v184, v222
	s_waitcnt lgkmcnt(0)
	v_max_f32_e32 v223, v223, v223
	v_max_f32_e32 v222, v222, v223
	v_max_f32_e32 v32, v222, v222
	v_max_f32_e32 v33, 0, v32
	v_exp_f32_e64 v34, -v33
	v_add_f32_e32 v119, v119, v33
	v_xor_b32_e32 v32, 0x80000000, v119
	v_sub_f32_e32 v79, v79, v33
	v_sub_f32_e32 v78, v78, v33
	v_sub_f32_e32 v77, v77, v33
	v_sub_f32_e32 v76, v76, v33
	v_sub_f32_e32 v75, v75, v33
	v_sub_f32_e32 v74, v74, v33
	v_sub_f32_e32 v73, v73, v33
	v_sub_f32_e32 v72, v72, v33
	v_sub_f32_e32 v71, v71, v33
	v_sub_f32_e32 v70, v70, v33
	v_sub_f32_e32 v69, v69, v33
	v_sub_f32_e32 v68, v68, v33
	v_sub_f32_e32 v67, v67, v33
	v_sub_f32_e32 v66, v66, v33
	v_sub_f32_e32 v65, v65, v33
	v_sub_f32_e32 v64, v64, v33
	v_sub_f32_e32 v63, v63, v33
	v_sub_f32_e32 v62, v62, v33
	v_sub_f32_e32 v61, v61, v33
	v_sub_f32_e32 v60, v60, v33
	v_sub_f32_e32 v59, v59, v33
	v_sub_f32_e32 v58, v58, v33
	v_sub_f32_e32 v57, v57, v33
	v_sub_f32_e32 v56, v56, v33
	v_sub_f32_e32 v55, v55, v33
	v_sub_f32_e32 v54, v54, v33
	v_sub_f32_e32 v53, v53, v33
	v_sub_f32_e32 v52, v52, v33
	v_sub_f32_e32 v51, v51, v33
	v_sub_f32_e32 v50, v50, v33
	v_sub_f32_e32 v49, v49, v33
	v_sub_f32_e32 v48, v48, v33
	v_pk_mul_f32 v[30:31], v[30:31], v[34:35] op_sel_hi:[1,0]
	v_pk_mul_f32 v[28:29], v[28:29], v[34:35] op_sel_hi:[1,0]
	v_pk_mul_f32 v[26:27], v[26:27], v[34:35] op_sel_hi:[1,0]
	v_pk_mul_f32 v[24:25], v[24:25], v[34:35] op_sel_hi:[1,0]
	v_pk_mul_f32 v[22:23], v[22:23], v[34:35] op_sel_hi:[1,0]
	v_pk_mul_f32 v[20:21], v[20:21], v[34:35] op_sel_hi:[1,0]
	v_pk_mul_f32 v[18:19], v[18:19], v[34:35] op_sel_hi:[1,0]
	v_pk_mul_f32 v[16:17], v[16:17], v[34:35] op_sel_hi:[1,0]
	v_pk_mul_f32 v[14:15], v[14:15], v[34:35] op_sel_hi:[1,0]
	v_pk_mul_f32 v[12:13], v[12:13], v[34:35] op_sel_hi:[1,0]
	v_pk_mul_f32 v[10:11], v[10:11], v[34:35] op_sel_hi:[1,0]
	v_pk_mul_f32 v[8:9], v[8:9], v[34:35] op_sel_hi:[1,0]
	v_pk_mul_f32 v[6:7], v[6:7], v[34:35] op_sel_hi:[1,0]
	v_pk_mul_f32 v[4:5], v[4:5], v[34:35] op_sel_hi:[1,0]
	v_pk_mul_f32 v[2:3], v[2:3], v[34:35] op_sel_hi:[1,0]
	v_pk_mul_f32 v[0:1], v[0:1], v[34:35] op_sel_hi:[1,0]
	v_mul_f32_e32 v118, v118, v34
	v_mov_b32_e32 v33, v32
	v_mov_b32_e32 v34, v32
	v_mov_b32_e32 v35, v32
	v_mov_b32_e32 v36, v32
	v_mov_b32_e32 v37, v32
	v_mov_b32_e32 v38, v32
	v_mov_b32_e32 v39, v32
	v_mov_b32_e32 v40, v32
	v_mov_b32_e32 v41, v32
	v_mov_b32_e32 v42, v32
	v_mov_b32_e32 v43, v32
	v_mov_b32_e32 v44, v32
	v_mov_b32_e32 v45, v32
	v_mov_b32_e32 v46, v32
	v_mov_b32_e32 v47, v32
; __device__ __forceinline__ unsigned cvt_pk_bf16(float lo, float hi) { typedef float f2 __attribute__((ext_vector_type(2))); typedef __bf16 b2 __attribute__((ext_vector_type(2))); f2 v = {lo, hi}; b2 b = __builtin_convertvector(v, b2); return __builtin_bit_cast(unsigned, b); }
; __device__ __forceinline__ v4i16_t vtr(LAS const char* p) { return __builtin_amdgcn_ds_read_tr16_b64_v4i16((LAS v4i16_t*)p); }
; #define MFMA32(a, b, c) __builtin_amdgcn_mfma_f32_32x32x16_bf16((a), (b), (c), 0, 0, 0)
; template <int DQK, int NSUB, int MODE>
; __device__ __forceinline__ void flash_unit(LAS char* L, const bf16_t* Qp, int qpitch, const bf16_t* Kp, int kpitch, const bf16_t* Vp, int vpitch,
;                                            bf16_t* Op, int opitch, float lam, float oscale, const float* subln) {
;     ...
; #pragma unroll
;                 for (int r = 0; r < 16; ++r) ph[r] = __builtin_amdgcn_exp2f(ph[r]);
;                 { typedef float f32x2_ __attribute__((ext_vector_type(2))); f32x2_ r2 = {ph[0], ph[1]};
; #pragma unroll
;                   for (int r = 2; r < 16; r += 2) r2 += (f32x2_){ph[r], ph[r + 1]};
;                   lrow[s] += r2[0] + r2[1]; }
;                 bf16x8 pf[2];
; #pragma unroll
;                 for (int k2 = 0; k2 < 2; ++k2) { u32x4 w;
; #pragma unroll
;                     for (int e = 0; e < 4; ++e) w[e] = cvt_pk_bf16(ph[8 * k2 + 2 * e], ph[8 * k2 + 2 * e + 1]);
;                     pf[k2] = __builtin_bit_cast(bf16x8, w); }
; #pragma unroll
;                 for (int db = 0; db < 2; ++db)
; #pragma unroll
;                     for (int k2 = 0; k2 < 2; ++k2) { const int ks = 2 * hf + k2; const v4i16_t lo = vtr(Vb + (16 * ks) * VPB + db * 64), hh = vtr(Vb + (16 * ks + 8) * VPB + db * 64);
;                         const bf16x8 vf = {lo[0], lo[1], lo[2], lo[3], hh[0], hh[1], hh[2], hh[3]};
;                         o[s][db] = MFMA32(vf, pf[k2], o[s][db]); }
;             }
;         }
;         if (t + 1 < SEQ / 64) { char* Kn = Lg + (buf ^ 1) * KBUF; *(u32x4*)(Kn + kl1) = rk1; if (has2) *(u32x4*)(Kn + kl2) = rk2; *(u32x4*)(Lg + OFF_V + (buf ^ 1) * VBUF + vl1) = rv1; }
;         __syncthreads();
.Lfc_614:
	v_exp_f32_e32 v64, v64
	v_exp_f32_e32 v65, v65
	v_exp_f32_e32 v220, v66
	v_exp_f32_e32 v221, v67
	v_exp_f32_e32 v68, v68
	v_exp_f32_e32 v69, v69
	v_exp_f32_e32 v70, v70
	v_exp_f32_e32 v71, v71
	v_exp_f32_e32 v72, v72
	v_exp_f32_e32 v73, v73
	v_exp_f32_e32 v74, v74
	v_exp_f32_e32 v75, v75
	v_pk_add_f32 v[66:67], v[64:65], v[220:221]
	v_exp_f32_e32 v76, v76
	v_exp_f32_e32 v77, v77
	v_pk_add_f32 v[66:67], v[68:69], v[66:67]
	v_exp_f32_e32 v78, v78
	v_exp_f32_e32 v79, v79
	v_pk_add_f32 v[66:67], v[70:71], v[66:67]
	v_pk_add_f32 v[66:67], v[72:73], v[66:67]
	v_cvt_pk_bf16_f32 v68, v68, v69
	v_pk_add_f32 v[66:67], v[74:75], v[66:67]
	v_cvt_pk_bf16_f32 v69, v70, v71
	v_pk_add_f32 v[66:67], v[76:77], v[66:67]
	v_cvt_pk_bf16_f32 v70, v72, v73
	v_pk_add_f32 v[222:223], v[78:79], v[66:67]
	v_cvt_pk_bf16_f32 v66, v64, v65
	v_cvt_pk_bf16_f32 v71, v74, v75
	v_cvt_pk_bf16_f32 v72, v76, v77
	v_cvt_pk_bf16_f32 v67, v220, v221
	v_cvt_pk_bf16_f32 v73, v78, v79
	v_add_f32_e32 v65, v222, v223
	s_waitcnt lgkmcnt(0)
	v_mfma_f32_32x32x16_bf16 v[0:15], v[204:207], v[66:69], v[0:15]
	v_add_f32_e32 v65, v118, v65
	v_max_f32_e32 v224, v49, v49
	v_max_f32_e32 v225, v48, v48
	v_max_f32_e32 v224, v225, v224
	v_mfma_f32_32x32x16_bf16 v[0:15], v[208:211], v[70:73], v[0:15]
	v_max3_f32 v224, v224, v50, v51
	v_max3_f32 v224, v224, v52, v53
	v_max3_f32 v224, v224, v54, v55
	v_max3_f32 v224, v224, v56, v57
	v_mfma_f32_32x32x16_bf16 v[16:31], v[212:215], v[66:69], v[16:31]
	v_max3_f32 v224, v224, v58, v59
	v_max3_f32 v224, v224, v60, v61
	v_max3_f32 v224, v224, v62, v63
	v_mfma_f32_32x32x16_bf16 v[16:31], v[216:219], v[70:73], v[16:31]
	v_cmp_lt_f32_e32 vcc, s61, v224
	s_cbranch_vccz .Lfc_616
	ds_bpermute_b32 v225, v184, v224
	s_waitcnt lgkmcnt(0)
	v_max_f32_e32 v225, v225, v225
	v_max_f32_e32 v224, v224, v225
	v_max_f32_e32 v32, v224, v224
	v_max_f32_e32 v33, 0, v32
	v_exp_f32_e64 v34, -v33
	v_add_f32_e32 v119, v119, v33
	v_xor_b32_e32 v32, 0x80000000, v119
	v_sub_f32_e32 v63, v63, v33
	v_sub_f32_e32 v62, v62, v33
	v_sub_f32_e32 v61, v61, v33
	v_sub_f32_e32 v60, v60, v33
	v_sub_f32_e32 v59, v59, v33
	v_sub_f32_e32 v58, v58, v33
	v_sub_f32_e32 v57, v57, v33
	v_sub_f32_e32 v56, v56, v33
	v_sub_f32_e32 v55, v55, v33
	v_sub_f32_e32 v54, v54, v33
	v_sub_f32_e32 v53, v53, v33
	v_sub_f32_e32 v52, v52, v33
	v_sub_f32_e32 v51, v51, v33
	v_sub_f32_e32 v50, v50, v33
	v_sub_f32_e32 v49, v49, v33
	v_sub_f32_e32 v48, v48, v33
	v_pk_mul_f32 v[14:15], v[14:15], v[34:35] op_sel_hi:[1,0]
	v_pk_mul_f32 v[12:13], v[12:13], v[34:35] op_sel_hi:[1,0]
	v_pk_mul_f32 v[10:11], v[10:11], v[34:35] op_sel_hi:[1,0]
	v_pk_mul_f32 v[8:9], v[8:9], v[34:35] op_sel_hi:[1,0]
	v_pk_mul_f32 v[6:7], v[6:7], v[34:35] op_sel_hi:[1,0]
	v_pk_mul_f32 v[4:5], v[4:5], v[34:35] op_sel_hi:[1,0]
	v_pk_mul_f32 v[2:3], v[2:3], v[34:35] op_sel_hi:[1,0]
	v_pk_mul_f32 v[0:1], v[0:1], v[34:35] op_sel_hi:[1,0]
	v_pk_mul_f32 v[30:31], v[30:31], v[34:35] op_sel_hi:[1,0]
	v_pk_mul_f32 v[28:29], v[28:29], v[34:35] op_sel_hi:[1,0]
	v_pk_mul_f32 v[26:27], v[26:27], v[34:35] op_sel_hi:[1,0]
	v_pk_mul_f32 v[24:25], v[24:25], v[34:35] op_sel_hi:[1,0]
	v_pk_mul_f32 v[22:23], v[22:23], v[34:35] op_sel_hi:[1,0]
	v_pk_mul_f32 v[20:21], v[20:21], v[34:35] op_sel_hi:[1,0]
	v_pk_mul_f32 v[18:19], v[18:19], v[34:35] op_sel_hi:[1,0]
	v_pk_mul_f32 v[16:17], v[16:17], v[34:35] op_sel_hi:[1,0]
	v_mul_f32_e32 v65, v65, v34
	v_mov_b32_e32 v33, v32
	v_mov_b32_e32 v34, v32
	v_mov_b32_e32 v35, v32
	v_mov_b32_e32 v36, v32
	v_mov_b32_e32 v37, v32
	v_mov_b32_e32 v38, v32
	v_mov_b32_e32 v39, v32
	v_mov_b32_e32 v40, v32
	v_mov_b32_e32 v41, v32
	v_mov_b32_e32 v42, v32
	v_mov_b32_e32 v43, v32
	v_mov_b32_e32 v44, v32
	v_mov_b32_e32 v45, v32
	v_mov_b32_e32 v46, v32
	v_mov_b32_e32 v47, v32
.Lfc_616:
	v_exp_f32_e32 v48, v48
	v_exp_f32_e32 v49, v49
	v_exp_f32_e32 v50, v50
	v_exp_f32_e32 v51, v51
	v_exp_f32_e32 v52, v52
	v_exp_f32_e32 v53, v53
	v_exp_f32_e32 v54, v54
	v_exp_f32_e32 v55, v55
	v_cvt_pk_bf16_f32 v66, v48, v49
	v_cvt_pk_bf16_f32 v67, v50, v51
	v_cvt_pk_bf16_f32 v68, v52, v53
	v_cvt_pk_bf16_f32 v69, v54, v55
	v_exp_f32_e32 v56, v56
	v_exp_f32_e32 v57, v57
	v_mfma_f32_32x32x16_bf16 v[0:15], v[132:135], v[66:69], v[0:15]
	v_exp_f32_e32 v58, v58
	v_exp_f32_e32 v59, v59
	v_exp_f32_e32 v60, v60
	v_exp_f32_e32 v61, v61
	v_exp_f32_e32 v62, v62
	v_exp_f32_e32 v63, v63
	v_cvt_pk_bf16_f32 v70, v56, v57
	v_cvt_pk_bf16_f32 v71, v58, v59
	v_cvt_pk_bf16_f32 v72, v60, v61
	v_cvt_pk_bf16_f32 v73, v62, v63
	s_andn2_b64 vcc, exec, s[14:15]
	v_mfma_f32_32x32x16_bf16 v[0:15], v[136:139], v[70:73], v[0:15]
	v_mfma_f32_32x32x16_bf16 v[16:31], v[144:147], v[66:69], v[16:31]
	v_mfma_f32_32x32x16_bf16 v[16:31], v[148:151], v[70:73], v[16:31]
	s_cbranch_vccnz .LBB0_607
	s_xor_b32 s14, s8, 1
	s_mul_i32 s8, s14, 0x3400
	s_add_i32 s15, s8, 0
	v_add_u32_e32 v64, s15, v127
	s_waitcnt vmcnt(0)
	ds_write_b128 v64, v[108:111]
	s_and_saveexec_b64 s[8:9], s[36:37]
	s_cbranch_execz .LBB0_606
	v_add_u32_e32 v64, s15, v126
	ds_write_b128 v64, v[104:107]
	s_branch .LBB0_606
